# attention XCD remap + SGU loads up front + attention z loads up front
# speedup vs baseline: 1.0094x; 1.0052x over previous
; __device__ __forceinline__ unsigned cvt_pk_bf16(float lo, float hi) { unsigned r; asm volatile("v_cvt_pk_bf16_f32 %0, %1, %2" : "=v"(r) : "v"(lo), "v"(hi)); return r; }
; __device__ __forceinline__ float bf_lo(unsigned w) { return __uint_as_float(w << 16); }
; __device__ __forceinline__ float bf_hi(unsigned w) { return __uint_as_float(w & 0xffff0000u); }
; __device__ __forceinline__ void attn_phase(LAS unsigned char* lds, const bf16_t* Q, const bf16_t* Kb, const bf16_t* VT, const bf16_t* Z, const float* kpart, bf16_t* Y, int G, int bid) {
;     ...
;             const float ltot = lsum + __shfl_xor(lsum, 32), inv = 1.0f / ltot;
; #pragma unroll
;             for (int dt = 0; dt < 4; ++dt)
; #pragma unroll
;                 for (int i4 = 0; i4 < 4; ++i4) {
;                     const size_t o = qoff + dt * 32 + i4 * 8 + hh * 4;
;                     const u32x2 zw = *(const u32x2*)(Z + o);
;                     u32x2 ow;
;                     ow.x = cvt_pk_bf16(O[dt][4 * i4 + 0] * inv * bf_lo(zw.x), O[dt][4 * i4 + 1] * inv * bf_hi(zw.x));
;                     ow.y = cvt_pk_bf16(O[dt][4 * i4 + 2] * inv * bf_lo(zw.y), O[dt][4 * i4 + 3] * inv * bf_hi(zw.y));
;                     *(u32x2*)(Y + o) = ow;
;                 }
.LBB0_640:
	v_or_b32_e32 v128, v212, v148
	v_mov_b32_e32 v129, v213
	v_lshl_add_u64 v[128:129], v[128:129], 1, s[28:29]
	global_load_dwordx2 v[218:219], v[128:129], off
	v_or_b32_e32 v128, v212, v154
	v_mov_b32_e32 v129, v213
	v_lshl_add_u64 v[128:129], v[128:129], 1, s[28:29]
	global_load_dwordx2 v[220:221], v[128:129], off
	v_or_b32_e32 v128, v212, v156
	v_mov_b32_e32 v129, v213
	v_lshl_add_u64 v[128:129], v[128:129], 1, s[28:29]
	global_load_dwordx2 v[222:223], v[128:129], off
	v_or_b32_e32 v128, v212, v158
	v_mov_b32_e32 v129, v213
	v_lshl_add_u64 v[128:129], v[128:129], 1, s[28:29]
	global_load_dwordx2 v[224:225], v[128:129], off
	v_or_b32_e32 v128, v212, v160
	v_mov_b32_e32 v129, v213
	v_lshl_add_u64 v[128:129], v[128:129], 1, s[28:29]
	global_load_dwordx2 v[226:227], v[128:129], off
	v_or_b32_e32 v128, v212, v162
	v_mov_b32_e32 v129, v213
	v_lshl_add_u64 v[128:129], v[128:129], 1, s[28:29]
	global_load_dwordx2 v[228:229], v[128:129], off
	v_or_b32_e32 v128, v212, v166
	v_mov_b32_e32 v129, v213
	v_lshl_add_u64 v[128:129], v[128:129], 1, s[28:29]
	global_load_dwordx2 v[230:231], v[128:129], off
	v_or_b32_e32 v128, v212, v168
	v_mov_b32_e32 v129, v213
	v_lshl_add_u64 v[128:129], v[128:129], 1, s[28:29]
	global_load_dwordx2 v[232:233], v[128:129], off
	v_or_b32_e32 v128, v212, v170
	v_mov_b32_e32 v129, v213
	v_lshl_add_u64 v[128:129], v[128:129], 1, s[28:29]
	global_load_dwordx2 v[234:235], v[128:129], off
	v_or_b32_e32 v128, v212, v172
	v_mov_b32_e32 v129, v213
	v_lshl_add_u64 v[128:129], v[128:129], 1, s[28:29]
	global_load_dwordx2 v[236:237], v[128:129], off
	v_or_b32_e32 v128, v212, v174
	v_mov_b32_e32 v129, v213
	v_lshl_add_u64 v[128:129], v[128:129], 1, s[28:29]
	global_load_dwordx2 v[238:239], v[128:129], off
	v_or_b32_e32 v128, v212, v176
	v_mov_b32_e32 v129, v213
	v_lshl_add_u64 v[128:129], v[128:129], 1, s[28:29]
	global_load_dwordx2 v[240:241], v[128:129], off
	v_or_b32_e32 v128, v212, v152
	v_mov_b32_e32 v129, v213
	v_lshl_add_u64 v[128:129], v[128:129], 1, s[28:29]
	global_load_dwordx2 v[242:243], v[128:129], off
	v_or_b32_e32 v128, v212, v178
	v_mov_b32_e32 v129, v213
	v_lshl_add_u64 v[128:129], v[128:129], 1, s[28:29]
	global_load_dwordx2 v[244:245], v[128:129], off
	v_or_b32_e32 v128, v212, v180
	v_mov_b32_e32 v129, v213
	v_lshl_add_u64 v[128:129], v[128:129], 1, s[28:29]
	global_load_dwordx2 v[246:247], v[128:129], off
	v_or_b32_e32 v128, v212, v182
	v_mov_b32_e32 v129, v213
	v_lshl_add_u64 v[128:129], v[128:129], 1, s[28:29]
	global_load_dwordx2 v[248:249], v[128:129], off
	v_or_b32_e32 v64, v212, v148
	v_mov_b32_e32 v65, v213
	v_lshlrev_b64 v[64:65], 1, v[64:65]
	v_lshl_add_u64 v[66:67], s[28:29], 0, v[64:65]
	v_and_b32_e32 v69, 64, v175
	v_xor_b32_e32 v68, 32, v175
	v_add_u32_e32 v69, 64, v69
	v_cmp_lt_i32_e32 vcc, v68, v69
	v_mov_b32_e32 v69, v213
	s_mov_b64 s[70:71], 0
	v_cndmask_b32_e32 v68, v175, v68, vcc
	v_lshlrev_b32_e32 v68, 2, v68
	ds_bpermute_b32 v70, v68, v215
	v_or_b32_e32 v68, v212, v154
	v_lshl_add_u64 v[68:69], v[68:69], 1, s[28:29]
	s_waitcnt lgkmcnt(0)
	v_add_f32_e32 v72, v215, v70
	v_div_scale_f32 v73, s[8:9], v72, v72, 1.0
	v_rcp_f32_e32 v74, v73
	v_lshl_add_u64 v[70:71], s[38:39], 0, v[64:65]
	v_div_scale_f32 v64, vcc, 1.0, v72, 1.0
	v_fma_f32 v65, -v73, v74, 1.0
	v_fmac_f32_e32 v74, v65, v74
	v_mul_f32_e32 v65, v64, v74
	v_fma_f32 v75, -v73, v65, v64
	v_fmac_f32_e32 v65, v75, v74
	v_fma_f32 v64, -v73, v65, v64
	v_div_fmas_f32 v64, v64, v74, v65
	v_div_fixup_f32 v64, v64, v72, 1.0
	v_mul_f32_e32 v48, v48, v64
	v_mul_f32_e32 v49, v49, v64
	v_mul_f32_e32 v50, v50, v64
	v_mul_f32_e32 v51, v51, v64
	v_mul_f32_e32 v53, v53, v64
	v_mul_f32_e32 v55, v55, v64
	v_mul_f32_e32 v52, v52, v64
	v_mul_f32_e32 v54, v54, v64
	v_mul_f32_e32 v32, v32, v64
	v_mul_f32_e32 v33, v33, v64
	v_mul_f32_e32 v34, v34, v64
	v_mul_f32_e32 v35, v35, v64
	v_mul_f32_e32 v37, v37, v64
	v_mul_f32_e32 v39, v39, v64
	v_mul_f32_e32 v36, v36, v64
	v_mul_f32_e32 v38, v38, v64
	v_mul_f32_e32 v16, v16, v64
	v_mul_f32_e32 v17, v17, v64
	v_mul_f32_e32 v18, v18, v64
	v_mul_f32_e32 v19, v19, v64
	v_mul_f32_e32 v21, v21, v64
	v_mul_f32_e32 v23, v23, v64
	v_mul_f32_e32 v20, v20, v64
	v_mul_f32_e32 v22, v22, v64
	v_mul_f32_e32 v0, v0, v64
	v_mul_f32_e32 v1, v1, v64
	v_mul_f32_e32 v2, v2, v64
	v_mul_f32_e32 v3, v3, v64
	v_mul_f32_e32 v5, v5, v64
	v_mul_f32_e32 v7, v7, v64
	v_mul_f32_e32 v4, v4, v64
	v_mul_f32_e32 v6, v6, v64
	s_and_b64 vcc, exec, s[0:1]
	s_waitcnt vmcnt(15)
	v_mov_b32_e32 v66, v218
	v_mov_b32_e32 v67, v219
	v_lshlrev_b32_e32 v65, 16, v66
	v_and_b32_e32 v66, 0xffff0000, v66
	v_lshlrev_b32_e32 v72, 16, v67
	v_and_b32_e32 v67, 0xffff0000, v67
	v_mul_f32_e32 v48, v48, v65
	v_mul_f32_e32 v49, v49, v66
	v_mul_f32_e32 v50, v50, v72
	v_mul_f32_e32 v51, v51, v67
	v_cvt_pk_bf16_f32 v48, v48, v49
	v_cvt_pk_bf16_f32 v49, v50, v51
	global_store_dwordx2 v[70:71], v[48:49], off
	v_lshl_add_u64 v[48:49], v[212:213], 0, v[148:149]
	v_or_b32_e32 v66, v212, v156
	v_mov_b32_e32 v67, v213
	v_lshl_add_u64 v[48:49], v[48:49], 1, s[38:39]
	v_lshl_add_u64 v[66:67], v[66:67], 1, s[28:29]
	s_waitcnt vmcnt(15)
	v_mov_b32_e32 v50, v220
	v_mov_b32_e32 v51, v221
	v_lshlrev_b32_e32 v65, 16, v50
	v_and_b32_e32 v50, 0xffff0000, v50
	v_lshlrev_b32_e32 v68, 16, v51
	v_and_b32_e32 v51, 0xffff0000, v51
	v_mul_f32_e32 v50, v53, v50
	v_mul_f32_e32 v51, v55, v51
	v_mul_f32_e32 v52, v52, v65
	v_mul_f32_e32 v53, v54, v68
	v_cvt_pk_bf16_f32 v50, v52, v50
	v_cvt_pk_bf16_f32 v51, v53, v51
	global_store_dwordx2 v[48:49], v[50:51], off offset:16
	v_mul_f32_e32 v54, v56, v64
	v_mul_f32_e32 v55, v57, v64
	v_mul_f32_e32 v56, v58, v64
	v_mul_f32_e32 v57, v59, v64
	v_or_b32_e32 v52, v212, v158
	v_mov_b32_e32 v53, v213
	v_lshl_add_u64 v[52:53], v[52:53], 1, s[28:29]
	s_waitcnt vmcnt(15)
; __device__ __forceinline__ unsigned cvt_pk_bf16(float lo, float hi) { unsigned r; asm volatile("v_cvt_pk_bf16_f32 %0, %1, %2" : "=v"(r) : "v"(lo), "v"(hi)); return r; }
; __device__ __forceinline__ float bf_lo(unsigned w) { return __uint_as_float(w << 16); }
; __device__ __forceinline__ float bf_hi(unsigned w) { return __uint_as_float(w & 0xffff0000u); }
; __device__ __forceinline__ void attn_phase(LAS unsigned char* lds, const bf16_t* Q, const bf16_t* Kb, const bf16_t* VT, const bf16_t* Z, const float* kpart, bf16_t* Y, int G, int bid) {
;     ...
;             for (int dt = 0; dt < 4; ++dt)
; #pragma unroll
;                 for (int i4 = 0; i4 < 4; ++i4) {
;                     const size_t o = qoff + dt * 32 + i4 * 8 + hh * 4;
;                     const u32x2 zw = *(const u32x2*)(Z + o);
;                     u32x2 ow;
;                     ow.x = cvt_pk_bf16(O[dt][4 * i4 + 0] * inv * bf_lo(zw.x), O[dt][4 * i4 + 1] * inv * bf_hi(zw.x));
;                     ow.y = cvt_pk_bf16(O[dt][4 * i4 + 2] * inv * bf_lo(zw.y), O[dt][4 * i4 + 3] * inv * bf_hi(zw.y));
;                     *(u32x2*)(Y + o) = ow;
;                 }
	v_mov_b32_e32 v50, v222
	v_mov_b32_e32 v51, v223
	v_lshlrev_b32_e32 v58, 16, v50
	v_and_b32_e32 v50, 0xffff0000, v50
	v_lshlrev_b32_e32 v59, 16, v51
	v_and_b32_e32 v51, 0xffff0000, v51
	v_mul_f32_e32 v50, v55, v50
	v_mul_f32_e32 v51, v57, v51
	v_mul_f32_e32 v54, v54, v58
	v_mul_f32_e32 v55, v56, v59
	v_cvt_pk_bf16_f32 v50, v54, v50
	v_cvt_pk_bf16_f32 v51, v55, v51
	global_store_dwordx2 v[48:49], v[50:51], off offset:32
	v_mul_f32_e32 v55, v61, v64
	v_mul_f32_e32 v57, v63, v64
	v_or_b32_e32 v52, v212, v160
	v_mov_b32_e32 v53, v213
	v_mul_f32_e32 v54, v60, v64
	v_mul_f32_e32 v56, v62, v64
	v_lshl_add_u64 v[52:53], v[52:53], 1, s[28:29]
	s_waitcnt vmcnt(15)
	v_mov_b32_e32 v50, v224
	v_mov_b32_e32 v51, v225
	v_lshlrev_b32_e32 v58, 16, v50
	v_and_b32_e32 v50, 0xffff0000, v50
	v_lshlrev_b32_e32 v59, 16, v51
	v_and_b32_e32 v51, 0xffff0000, v51
	v_mul_f32_e32 v50, v55, v50
	v_mul_f32_e32 v51, v57, v51
	v_mul_f32_e32 v54, v54, v58
	v_mul_f32_e32 v55, v56, v59
	v_cvt_pk_bf16_f32 v50, v54, v50
	v_cvt_pk_bf16_f32 v51, v55, v51
	global_store_dwordx2 v[48:49], v[50:51], off offset:48
	v_or_b32_e32 v52, v212, v162
	v_mov_b32_e32 v53, v213
	v_lshl_add_u64 v[52:53], v[52:53], 1, s[28:29]
	s_waitcnt vmcnt(15)
	v_mov_b32_e32 v50, v226
	v_mov_b32_e32 v51, v227
	v_lshlrev_b32_e32 v54, 16, v50
	v_and_b32_e32 v50, 0xffff0000, v50
	v_lshlrev_b32_e32 v55, 16, v51
	v_and_b32_e32 v51, 0xffff0000, v51
	v_mul_f32_e32 v32, v32, v54
	v_mul_f32_e32 v33, v33, v50
	v_mul_f32_e32 v34, v34, v55
	v_mul_f32_e32 v35, v35, v51
	v_cvt_pk_bf16_f32 v32, v32, v33
	v_cvt_pk_bf16_f32 v33, v34, v35
	global_store_dwordx2 v[48:49], v[32:33], off offset:64
	v_or_b32_e32 v34, v212, v166
	v_mov_b32_e32 v35, v213
	v_lshl_add_u64 v[34:35], v[34:35], 1, s[28:29]
	s_waitcnt vmcnt(15)
	v_mov_b32_e32 v32, v228
	v_mov_b32_e32 v33, v229
	v_lshlrev_b32_e32 v50, 16, v32
	v_and_b32_e32 v32, 0xffff0000, v32
	v_lshlrev_b32_e32 v51, 16, v33
	v_and_b32_e32 v33, 0xffff0000, v33
	v_mul_f32_e32 v32, v37, v32
	v_mul_f32_e32 v33, v39, v33
	v_mul_f32_e32 v36, v36, v50
	v_mul_f32_e32 v37, v38, v51
	v_cvt_pk_bf16_f32 v32, v36, v32
	v_cvt_pk_bf16_f32 v33, v37, v33
	global_store_dwordx2 v[48:49], v[32:33], off offset:80
	v_mul_f32_e32 v36, v40, v64
	v_mul_f32_e32 v37, v41, v64
	v_mul_f32_e32 v39, v43, v64
	v_or_b32_e32 v34, v212, v168
	v_mov_b32_e32 v35, v213
	v_mul_f32_e32 v38, v42, v64
	v_lshl_add_u64 v[34:35], v[34:35], 1, s[28:29]
	s_waitcnt vmcnt(15)
	v_mov_b32_e32 v32, v230
	v_mov_b32_e32 v33, v231
	v_lshlrev_b32_e32 v40, 16, v32
	v_and_b32_e32 v32, 0xffff0000, v32
	v_lshlrev_b32_e32 v41, 16, v33
	v_and_b32_e32 v33, 0xffff0000, v33
	v_mul_f32_e32 v32, v37, v32
	v_mul_f32_e32 v33, v39, v33
	v_mul_f32_e32 v36, v36, v40
	v_mul_f32_e32 v37, v38, v41
	v_cvt_pk_bf16_f32 v32, v36, v32
	v_cvt_pk_bf16_f32 v33, v37, v33
	global_store_dwordx2 v[48:49], v[32:33], off offset:96
	v_mul_f32_e32 v37, v45, v64
	v_mul_f32_e32 v39, v47, v64
	v_or_b32_e32 v34, v212, v170
	v_mov_b32_e32 v35, v213
	v_mul_f32_e32 v36, v44, v64
	v_mul_f32_e32 v38, v46, v64
	v_lshl_add_u64 v[34:35], v[34:35], 1, s[28:29]
	s_waitcnt vmcnt(15)
	v_mov_b32_e32 v32, v232
	v_mov_b32_e32 v33, v233
	v_lshlrev_b32_e32 v40, 16, v32
	v_and_b32_e32 v32, 0xffff0000, v32
	v_lshlrev_b32_e32 v41, 16, v33
	v_and_b32_e32 v33, 0xffff0000, v33
	v_mul_f32_e32 v32, v37, v32
	v_mul_f32_e32 v33, v39, v33
	v_mul_f32_e32 v36, v36, v40
	v_mul_f32_e32 v37, v38, v41
	v_cvt_pk_bf16_f32 v32, v36, v32
	v_cvt_pk_bf16_f32 v33, v37, v33
	global_store_dwordx2 v[48:49], v[32:33], off offset:112
	v_or_b32_e32 v34, v212, v172
	v_mov_b32_e32 v35, v213
	v_lshl_add_u64 v[34:35], v[34:35], 1, s[28:29]
	s_waitcnt vmcnt(15)
	v_mov_b32_e32 v32, v234
	v_mov_b32_e32 v33, v235
	v_lshlrev_b32_e32 v36, 16, v32
	v_and_b32_e32 v32, 0xffff0000, v32
	v_lshlrev_b32_e32 v37, 16, v33
	v_and_b32_e32 v33, 0xffff0000, v33
	v_mul_f32_e32 v16, v16, v36
	v_mul_f32_e32 v17, v17, v32
	v_mul_f32_e32 v18, v18, v37
	v_mul_f32_e32 v19, v19, v33
	v_cvt_pk_bf16_f32 v16, v16, v17
	v_cvt_pk_bf16_f32 v17, v18, v19
	global_store_dwordx2 v[48:49], v[16:17], off offset:128
	v_or_b32_e32 v18, v212, v174
	v_mov_b32_e32 v19, v213
	v_lshl_add_u64 v[18:19], v[18:19], 1, s[28:29]
	s_waitcnt vmcnt(15)
; __device__ __forceinline__ unsigned cvt_pk_bf16(float lo, float hi) { unsigned r; asm volatile("v_cvt_pk_bf16_f32 %0, %1, %2" : "=v"(r) : "v"(lo), "v"(hi)); return r; }
; __device__ __forceinline__ float bf_lo(unsigned w) { return __uint_as_float(w << 16); }
; __device__ __forceinline__ float bf_hi(unsigned w) { return __uint_as_float(w & 0xffff0000u); }
; __device__ __forceinline__ void attn_phase(LAS unsigned char* lds, const bf16_t* Q, const bf16_t* Kb, const bf16_t* VT, const bf16_t* Z, const float* kpart, bf16_t* Y, int G, int bid) {
;     ...
;             for (int dt = 0; dt < 4; ++dt)
; #pragma unroll
;                 for (int i4 = 0; i4 < 4; ++i4) {
;                     const size_t o = qoff + dt * 32 + i4 * 8 + hh * 4;
;                     const u32x2 zw = *(const u32x2*)(Z + o);
;                     u32x2 ow;
;                     ow.x = cvt_pk_bf16(O[dt][4 * i4 + 0] * inv * bf_lo(zw.x), O[dt][4 * i4 + 1] * inv * bf_hi(zw.x));
;                     ow.y = cvt_pk_bf16(O[dt][4 * i4 + 2] * inv * bf_lo(zw.y), O[dt][4 * i4 + 3] * inv * bf_hi(zw.y));
;                     *(u32x2*)(Y + o) = ow;
;                 }
	v_mov_b32_e32 v16, v236
	v_mov_b32_e32 v17, v237
	v_lshlrev_b32_e32 v32, 16, v16
	v_and_b32_e32 v16, 0xffff0000, v16
	v_lshlrev_b32_e32 v33, 16, v17
	v_and_b32_e32 v17, 0xffff0000, v17
	v_mul_f32_e32 v16, v21, v16
	v_mul_f32_e32 v17, v23, v17
	v_mul_f32_e32 v20, v20, v32
	v_mul_f32_e32 v21, v22, v33
	v_cvt_pk_bf16_f32 v16, v20, v16
	v_cvt_pk_bf16_f32 v17, v21, v17
	global_store_dwordx2 v[48:49], v[16:17], off offset:144
	v_mul_f32_e32 v20, v24, v64
	v_mul_f32_e32 v21, v25, v64
	v_mul_f32_e32 v23, v27, v64
	v_or_b32_e32 v18, v212, v176
	v_mov_b32_e32 v19, v213
	v_mul_f32_e32 v22, v26, v64
	v_lshl_add_u64 v[18:19], v[18:19], 1, s[28:29]
	s_waitcnt vmcnt(15)
	v_mov_b32_e32 v16, v238
	v_mov_b32_e32 v17, v239
	v_lshlrev_b32_e32 v24, 16, v16
	v_and_b32_e32 v16, 0xffff0000, v16
	v_lshlrev_b32_e32 v25, 16, v17
	v_and_b32_e32 v17, 0xffff0000, v17
	v_mul_f32_e32 v16, v21, v16
	v_mul_f32_e32 v17, v23, v17
	v_mul_f32_e32 v20, v20, v24
	v_mul_f32_e32 v21, v22, v25
	v_cvt_pk_bf16_f32 v16, v20, v16
	v_cvt_pk_bf16_f32 v17, v21, v17
	global_store_dwordx2 v[48:49], v[16:17], off offset:160
	v_mul_f32_e32 v21, v29, v64
	v_mul_f32_e32 v23, v31, v64
	v_or_b32_e32 v18, v212, v152
	v_mov_b32_e32 v19, v213
	v_mul_f32_e32 v20, v28, v64
	v_mul_f32_e32 v22, v30, v64
	v_lshl_add_u64 v[18:19], v[18:19], 1, s[28:29]
	s_waitcnt vmcnt(15)
	v_mov_b32_e32 v16, v240
	v_mov_b32_e32 v17, v241
	v_lshlrev_b32_e32 v24, 16, v16
	v_and_b32_e32 v16, 0xffff0000, v16
	v_lshlrev_b32_e32 v25, 16, v17
	v_and_b32_e32 v17, 0xffff0000, v17
	v_mul_f32_e32 v16, v21, v16
	v_mul_f32_e32 v17, v23, v17
	v_mul_f32_e32 v20, v20, v24
	v_mul_f32_e32 v21, v22, v25
	v_cvt_pk_bf16_f32 v16, v20, v16
	v_cvt_pk_bf16_f32 v17, v21, v17
	global_store_dwordx2 v[48:49], v[16:17], off offset:176
	v_or_b32_e32 v18, v212, v178
	v_mov_b32_e32 v19, v213
	v_lshl_add_u64 v[18:19], v[18:19], 1, s[28:29]
	s_waitcnt vmcnt(15)
	v_mov_b32_e32 v16, v242
	v_mov_b32_e32 v17, v243
	v_lshlrev_b32_e32 v20, 16, v16
	v_and_b32_e32 v16, 0xffff0000, v16
	v_lshlrev_b32_e32 v21, 16, v17
	v_and_b32_e32 v17, 0xffff0000, v17
	v_mul_f32_e32 v0, v0, v20
	v_mul_f32_e32 v1, v1, v16
	v_mul_f32_e32 v2, v2, v21
	v_mul_f32_e32 v3, v3, v17
	v_cvt_pk_bf16_f32 v0, v0, v1
	v_cvt_pk_bf16_f32 v1, v2, v3
	global_store_dwordx2 v[48:49], v[0:1], off offset:192
	v_or_b32_e32 v2, v212, v180
	v_mov_b32_e32 v3, v213
	v_lshl_add_u64 v[2:3], v[2:3], 1, s[28:29]
	v_or_b32_e32 v212, v212, v182
	s_waitcnt vmcnt(15)
	v_mov_b32_e32 v0, v244
	v_mov_b32_e32 v1, v245
	v_lshlrev_b32_e32 v16, 16, v0
	v_and_b32_e32 v0, 0xffff0000, v0
	v_lshlrev_b32_e32 v17, 16, v1
	v_and_b32_e32 v1, 0xffff0000, v1
	v_mul_f32_e32 v0, v5, v0
	v_mul_f32_e32 v1, v7, v1
	v_mul_f32_e32 v4, v4, v16
	v_mul_f32_e32 v5, v6, v17
	v_cvt_pk_bf16_f32 v0, v4, v0
	v_cvt_pk_bf16_f32 v1, v5, v1
	global_store_dwordx2 v[48:49], v[0:1], off offset:208
	v_mul_f32_e32 v4, v8, v64
	v_mul_f32_e32 v5, v9, v64
	v_mul_f32_e32 v7, v11, v64
	v_mul_f32_e32 v6, v10, v64
	v_lshl_add_u64 v[2:3], v[212:213], 1, s[28:29]
	s_waitcnt vmcnt(15)
	v_mov_b32_e32 v0, v246
	v_mov_b32_e32 v1, v247
	v_lshlrev_b32_e32 v8, 16, v0
	v_and_b32_e32 v0, 0xffff0000, v0
	v_lshlrev_b32_e32 v9, 16, v1
	v_and_b32_e32 v1, 0xffff0000, v1
	v_mul_f32_e32 v0, v5, v0
	v_mul_f32_e32 v1, v7, v1
	v_mul_f32_e32 v4, v4, v8
	v_mul_f32_e32 v5, v6, v9
	v_cvt_pk_bf16_f32 v0, v4, v0
	v_cvt_pk_bf16_f32 v1, v5, v1
	global_store_dwordx2 v[48:49], v[0:1], off offset:224
	v_mul_f32_e32 v3, v13, v64
	v_mul_f32_e32 v5, v15, v64
	v_mul_f32_e32 v2, v12, v64
	v_mul_f32_e32 v4, v14, v64
	s_waitcnt vmcnt(15)
	v_mov_b32_e32 v0, v248
	v_mov_b32_e32 v1, v249
	v_lshlrev_b32_e32 v6, 16, v0
	v_and_b32_e32 v0, 0xffff0000, v0
	v_lshlrev_b32_e32 v7, 16, v1
	v_and_b32_e32 v1, 0xffff0000, v1
	v_mul_f32_e32 v0, v3, v0
	v_mul_f32_e32 v1, v5, v1
	v_mul_f32_e32 v2, v2, v6
	v_mul_f32_e32 v3, v4, v7
	v_cvt_pk_bf16_f32 v0, v2, v0
	v_cvt_pk_bf16_f32 v1, v3, v1
	global_store_dwordx2 v[48:49], v[0:1], off offset:240
	s_cbranch_vccnz .LBB0_638
